# attention K/V LDS ring 3 -> 4 stages: one workgroup barrier per pair of key tiles (barrier between the two unrolled steps kept only on the exit path)
# baseline (speedup 1.0000x reference)
; template <int MODE>
; DI void flash_pass(AState& st, const bf16x8* qf, u64 tmask, u64 wmask,
;                    const bf16_t* kbase, size_t kld, const bf16_t* kpe, const bf16_t* vtbase, const float* fbias,
;                    int tq, u64 mysel, bf16_t* smem) {
;     ...
;   auto step = [&](auto setc) -> bool {
;     const int t4 = pop();
;     sstore(stg == 0 ? 2 : stg - 1, setc);
;     gload(t4 >= 0 ? t4 : t0, setc);
;     __builtin_amdgcn_sched_barrier(0);
;     compute(t0, stg);
;     __syncthreads();
;     if (t1 < 0) return true;
;     t0 = t1; t1 = t2; t2 = t3; t3 = t4; stg = stg == 2 ? 0 : stg + 1;
;     return false;
;   };
;   for (;;) {
;     if (step(S0{})) break;
;     if (step(S1{})) break;
.LBB0_605:
	s_or_b64 exec, exec, s[14:15]
	s_add_u32 s2, s10, -1
	s_addc_u32 s3, s11, -1
	s_and_b64 s[10:11], s[2:3], s[10:11]
	s_and_b64 s[2:3], s[12:13], exec
	s_cselect_b32 s4, -1, s28
	s_and_b64 s[2:3], s[8:9], exec
	s_cselect_b32 s5, -1, s25
	s_cmp_lt_i32 s22, 0
	s_cselect_b64 s[2:3], -1, 0
	s_add_i32 s8, s27, 1
	s_nop 0
	s_and_b32 s14, s8, 3
	s_waitcnt lgkmcnt(0)
	s_barrier

; template <int MODE>
; DI void flash_pass(AState& st, const bf16x8* qf, u64 tmask, u64 wmask,
;                    const bf16_t* kbase, size_t kld, const bf16_t* kpe, const bf16_t* vtbase, const float* fbias,
;                    int tq, u64 mysel, bf16_t* smem) {
;     ...
;   auto sstore = [&](int stg, auto setc) {
;     constexpr int S = decltype(setc)::value;
;     bf16_t* Ks = smem + stg * C::STAGE; bf16_t* Vs = Ks + C::K_ELEMS;
; #pragma unroll
;     for (int i = 0; i < C::KCH; ++i) {
;       const int c = tid + NTHR * i;
;       if (c < C::NKC) {
;         if constexpr (MODE == M_MLA) { const int key = c / 12, dc = c % 12; *(u32x4*)(Ks + key * C::KLD + dc * 8) = rk[S][i]; }
;         else { const int key = c >> 3, dc = c & 7; *(u32x4*)(Ks + key * C::KLD + dc * 8) = rk[S][i]; }
;       }
;     ...
;   auto step = [&](auto setc) -> bool {
;     const int t4 = pop();
;     sstore(stg == 0 ? 2 : stg - 1, setc);
.LBB0_607:
	s_mul_i32 s4, s14, 0x2480
	s_xor_b32 s2, s14, 2
	s_mul_i32 s2, s2, 0x2480
	s_nop 0
	s_lshl_b32 s5, s2, 1
	s_and_saveexec_b64 s[2:3], s[0:1]
	s_cbranch_execz .LBB0_609
	v_add3_u32 v0, s5, v126, v114
	s_waitcnt vmcnt(1)
	ds_write_b128 v0, v[100:103]

; template <int MODE>
; DI void flash_pass(AState& st, const bf16x8* qf, u64 tmask, u64 wmask,
;                    const bf16_t* kbase, size_t kld, const bf16_t* kpe, const bf16_t* vtbase, const float* fbias,
;                    int tq, u64 mysel, bf16_t* smem) {
;     ...
;   auto step = [&](auto setc) -> bool {
;     const int t4 = pop();
;     sstore(stg == 0 ? 2 : stg - 1, setc);
;     ...
;     compute(t0, stg);
;     __syncthreads();
;     if (t1 < 0) return true;
;     t0 = t1; t1 = t2; t2 = t3; t3 = t4; stg = stg == 2 ? 0 : stg + 1;
.LBB0_616:
	s_or_b64 exec, exec, s[12:13]
	s_cmp_lt_i32 s26, 0
	s_mov_b64 s[2:3], -1
	s_nop 0
	s_nop 0
	s_cbranch_scc1 .Lxb0
	s_add_i32 s2, s14, 1
	s_nop 0
	s_and_b32 s27, s2, 3
	s_mul_i32 s4, s27, 0x2480
	s_xor_b32 s2, s27, 2
	s_mul_i32 s2, s2, 0x2480
	s_nop 0
	s_lshl_b32 s5, s2, 1
	s_and_saveexec_b64 s[2:3], s[0:1]
	s_cbranch_execz .LBB0_619
	v_add3_u32 v0, s5, v126, v114
	s_waitcnt vmcnt(3)
	ds_write_b128 v0, v[108:111]

; template <int MODE>
; DI void flash_pass(AState& st, const bf16x8* qf, u64 tmask, u64 wmask,
;                    const bf16_t* kbase, size_t kld, const bf16_t* kpe, const bf16_t* vtbase, const float* fbias,
;                    int tq, u64 mysel, bf16_t* smem) {
;     ...
;     compute(t0, stg);
;     __syncthreads();
;     if (t1 < 0) return true;
.Lxb0:
	s_waitcnt lgkmcnt(0)
	s_barrier

; template <int MODE>
; DI void flash_pass(AState& st, const bf16x8* qf, u64 tmask, u64 wmask,
;                    const bf16_t* kbase, size_t kld, const bf16_t* kpe, const bf16_t* vtbase, const float* fbias,
;                    int tq, u64 mysel, bf16_t* smem) {
;     ...
;   auto sstore = [&](int stg, auto setc) {
;     constexpr int S = decltype(setc)::value;
;     bf16_t* Ks = smem + stg * C::STAGE; bf16_t* Vs = Ks + C::K_ELEMS;
; #pragma unroll
;     for (int i = 0; i < C::KCH; ++i) {
;       const int c = tid + NTHR * i;
;       if (c < C::NKC) {
;         if constexpr (MODE == M_MLA) { const int key = c / 12, dc = c % 12; *(u32x4*)(Ks + key * C::KLD + dc * 8) = rk[S][i]; }
;         else { const int key = c >> 3, dc = c & 7; *(u32x4*)(Ks + key * C::KLD + dc * 8) = rk[S][i]; }
;       }
;     ...
;   auto step = [&](auto setc) -> bool {
;     const int t4 = pop();
;     sstore(stg == 0 ? 2 : stg - 1, setc);
.LBB0_632:
	s_mul_i32 s4, s12, 0x2480
	s_xor_b32 s2, s12, 2
	s_mul_i32 s2, s2, 0x2480
	s_nop 0
	s_lshl_b32 s5, s2, 1
	s_and_saveexec_b64 s[2:3], s[0:1]
	s_cbranch_execz .LBB0_634
	v_add3_u32 v0, s5, v183, v168
	s_waitcnt vmcnt(1)
	ds_write_b128 v0, v[148:151]

; template <int MODE>
; DI void flash_pass(AState& st, const bf16x8* qf, u64 tmask, u64 wmask,
;                    const bf16_t* kbase, size_t kld, const bf16_t* kpe, const bf16_t* vtbase, const float* fbias,
;                    int tq, u64 mysel, bf16_t* smem) {
;     ...
;   auto step = [&](auto setc) -> bool {
;     const int t4 = pop();
;     sstore(stg == 0 ? 2 : stg - 1, setc);
;     ...
;     compute(t0, stg);
;     __syncthreads();
;     if (t1 < 0) return true;
;     t0 = t1; t1 = t2; t2 = t3; t3 = t4; stg = stg == 2 ? 0 : stg + 1;
.LBB0_645:
	s_cmp_lt_i32 s18, 0
	s_mov_b64 s[2:3], -1
	s_nop 0
	s_nop 0
	s_cbranch_scc1 .Lxb1
	s_add_i32 s2, s12, 1
	s_nop 0
	s_and_b32 s19, s2, 3
	s_mul_i32 s4, s19, 0x2480
	s_xor_b32 s2, s19, 2
	s_mul_i32 s2, s2, 0x2480
	s_nop 0
	s_lshl_b32 s5, s2, 1
	s_and_saveexec_b64 s[2:3], s[0:1]
	s_cbranch_execz .LBB0_648
	v_add3_u32 v0, s5, v183, v168
	s_waitcnt vmcnt(3)
	ds_write_b128 v0, v[156:159]

; template <int MODE>
; DI void flash_pass(AState& st, const bf16x8* qf, u64 tmask, u64 wmask,
;                    const bf16_t* kbase, size_t kld, const bf16_t* kpe, const bf16_t* vtbase, const float* fbias,
;                    int tq, u64 mysel, bf16_t* smem) {
;     ...
;     if (t1 < 0) return true;
;     t0 = t1; t1 = t2; t2 = t3; t3 = t4; stg = stg == 2 ? 0 : stg + 1;
;     return false;
;   };
;   for (;;) {
;     if (step(S0{})) break;
;     if (step(S1{})) break;
.LBB0_660:
	s_add_u32 s2, s10, -1
	s_addc_u32 s3, s11, -1
	s_and_b64 s[10:11], s[2:3], s[10:11]
	s_and_b64 s[2:3], s[12:13], exec
	s_cselect_b32 s4, -1, s20
	s_and_b64 s[2:3], s[8:9], exec
	s_cselect_b32 s5, -1, s17
	s_cmp_lt_i32 s15, 0
	s_cselect_b64 s[2:3], -1, 0
	s_add_i32 s8, s19, 1
	s_nop 0
	s_waitcnt lgkmcnt(0)
	s_barrier
	s_and_b32 s12, s8, 3
	s_and_b64 vcc, exec, s[2:3]
	s_cbranch_vccnz .LBB0_663

; template <int MODE>
; DI void flash_pass(AState& st, const bf16x8* qf, u64 tmask, u64 wmask,
;                    const bf16_t* kbase, size_t kld, const bf16_t* kpe, const bf16_t* vtbase, const float* fbias,
;                    int tq, u64 mysel, bf16_t* smem) {
;     ...
;   auto step = [&](auto setc) -> bool {
;     const int t4 = pop();
;     sstore(stg == 0 ? 2 : stg - 1, setc);
;     gload(t4 >= 0 ? t4 : t0, setc);
;     __builtin_amdgcn_sched_barrier(0);
;     compute(t0, stg);
;     __syncthreads();
;     if (t1 < 0) return true;
;     t0 = t1; t1 = t2; t2 = t3; t3 = t4; stg = stg == 2 ? 0 : stg + 1;
;     return false;
;   };
;   for (;;) {
;     if (step(S0{})) break;
;     if (step(S1{})) break;
.LBB0_678:
	s_or_b64 exec, exec, s[82:83]
	s_add_u32 s4, s78, -1
	s_addc_u32 s5, s79, -1
	s_and_b64 s[78:79], s[4:5], s[78:79]
	s_and_b64 s[4:5], s[80:81], exec
	s_cselect_b32 s6, -1, s91
	s_and_b64 s[4:5], s[76:77], exec
	s_cselect_b32 s7, -1, s96
	s_cmp_lt_i32 s94, 0
	s_cselect_b64 s[4:5], -1, 0
	s_add_i32 s8, s89, 1
	s_nop 0
	s_and_b32 s82, s8, 3
	s_waitcnt lgkmcnt(0)
	s_barrier

; template <int MODE>
; DI void flash_pass(AState& st, const bf16x8* qf, u64 tmask, u64 wmask,
;                    const bf16_t* kbase, size_t kld, const bf16_t* kpe, const bf16_t* vtbase, const float* fbias,
;                    int tq, u64 mysel, bf16_t* smem) {
;     ...
;   auto sstore = [&](int stg, auto setc) {
;     constexpr int S = decltype(setc)::value;
;     bf16_t* Ks = smem + stg * C::STAGE; bf16_t* Vs = Ks + C::K_ELEMS;
; #pragma unroll
;     for (int i = 0; i < C::KCH; ++i) {
;       const int c = tid + NTHR * i;
;       if (c < C::NKC) {
;         if constexpr (MODE == M_MLA) { const int key = c / 12, dc = c % 12; *(u32x4*)(Ks + key * C::KLD + dc * 8) = rk[S][i]; }
;         else { const int key = c >> 3, dc = c & 7; *(u32x4*)(Ks + key * C::KLD + dc * 8) = rk[S][i]; }
;       }
;     ...
;   auto step = [&](auto setc) -> bool {
;     const int t4 = pop();
;     sstore(stg == 0 ? 2 : stg - 1, setc);
.LBB0_680:
	s_mul_i32 s6, s82, 0x2480
	s_xor_b32 s4, s82, 2
	s_mul_i32 s4, s4, 0x2480
	s_nop 0
	s_lshl_b32 s7, s4, 1
	s_and_saveexec_b64 s[4:5], s[0:1]
	s_cbranch_execz .LBB0_682
	v_add3_u32 v0, s7, v167, v148
	s_waitcnt vmcnt(2)
	ds_write_b128 v0, v[128:131]

; template <int MODE>
; DI void flash_pass(AState& st, const bf16x8* qf, u64 tmask, u64 wmask,
;                    const bf16_t* kbase, size_t kld, const bf16_t* kpe, const bf16_t* vtbase, const float* fbias,
;                    int tq, u64 mysel, bf16_t* smem) {
;     ...
;   auto step = [&](auto setc) -> bool {
;     const int t4 = pop();
;     sstore(stg == 0 ? 2 : stg - 1, setc);
;     ...
;     compute(t0, stg);
;     __syncthreads();
;     if (t1 < 0) return true;
;     t0 = t1; t1 = t2; t2 = t3; t3 = t4; stg = stg == 2 ? 0 : stg + 1;
.LBB0_693:
	s_or_b64 exec, exec, s[80:81]
	s_cmp_lt_i32 s97, 0
	s_mov_b64 s[4:5], -1
	s_nop 0
	s_nop 0
	s_cbranch_scc1 .Lxb2
	s_add_i32 s4, s82, 1
	s_nop 0
	s_and_b32 s89, s4, 3
	s_mul_i32 s6, s89, 0x2480
	s_xor_b32 s4, s89, 2
	s_mul_i32 s4, s4, 0x2480
	s_nop 0
	s_lshl_b32 s7, s4, 1
	s_and_saveexec_b64 s[4:5], s[0:1]
	s_cbranch_execz .LBB0_696
	v_add3_u32 v0, s7, v167, v148
	s_waitcnt vmcnt(5)
	ds_write_b128 v0, v[140:143]

; template <int MODE>
; DI void flash_pass(AState& st, const bf16x8* qf, u64 tmask, u64 wmask,
;                    const bf16_t* kbase, size_t kld, const bf16_t* kpe, const bf16_t* vtbase, const float* fbias,
;                    int tq, u64 mysel, bf16_t* smem) {
;     ...
;   auto sstore = [&](int stg, auto setc) {
;     constexpr int S = decltype(setc)::value;
;     bf16_t* Ks = smem + stg * C::STAGE; bf16_t* Vs = Ks + C::K_ELEMS;
; #pragma unroll
;     for (int i = 0; i < C::KCH; ++i) {
;       const int c = tid + NTHR * i;
;       if (c < C::NKC) {
;         if constexpr (MODE == M_MLA) { const int key = c / 12, dc = c % 12; *(u32x4*)(Ks + key * C::KLD + dc * 8) = rk[S][i]; }
;         else { const int key = c >> 3, dc = c & 7; *(u32x4*)(Ks + key * C::KLD + dc * 8) = rk[S][i]; }
;       }
;     ...
;   auto step = [&](auto setc) -> bool {
;     const int t4 = pop();
;     sstore(stg == 0 ? 2 : stg - 1, setc);
.LBB0_750:
	s_mul_i32 s14, s18, 0x2c80
	s_xor_b32 s8, s18, 2
	s_mul_i32 s8, s8, 0x2c80
	s_nop 0
	s_lshl_b32 s12, s8, 1
	s_and_saveexec_b64 s[8:9], s[4:5]
	s_cbranch_execz .LBB0_752
	v_lshlrev_b32_e32 v2, 1, v165
	v_lshlrev_b32_e32 v3, 1, v166
	v_add3_u32 v2, s12, v2, v3
	s_waitcnt vmcnt(2)
	ds_write_b128 v2, v[120:123]

; template <int MODE>
; DI void flash_pass(AState& st, const bf16x8* qf, u64 tmask, u64 wmask,
;                    const bf16_t* kbase, size_t kld, const bf16_t* kpe, const bf16_t* vtbase, const float* fbias,
;                    int tq, u64 mysel, bf16_t* smem) {
;     ...
;   auto step = [&](auto setc) -> bool {
;     const int t4 = pop();
;     sstore(stg == 0 ? 2 : stg - 1, setc);
;     ...
;     compute(t0, stg);
;     __syncthreads();
;     if (t1 < 0) return true;
;     t0 = t1; t1 = t2; t2 = t3; t3 = t4; stg = stg == 2 ? 0 : stg + 1;
.LBB0_761:
	s_or_b64 exec, exec, s[12:13]
	s_cmp_lt_i32 s22, 0
	s_mov_b64 s[14:15], -1
	s_nop 0
	s_nop 0
	s_cbranch_scc1 .Lxb3
	s_add_i32 s12, s18, 1
	s_nop 0
	s_and_b32 s18, s12, 3
	s_mul_i32 s21, s18, 0x2c80
	s_xor_b32 s12, s18, 2
	s_mul_i32 s12, s12, 0x2c80
	s_nop 0
	s_lshl_b32 s14, s12, 1
	s_and_saveexec_b64 s[12:13], s[4:5]
	s_cbranch_execz .LBB0_764
	v_lshlrev_b32_e32 v2, 1, v165
	v_lshlrev_b32_e32 v3, 1, v166
	v_add3_u32 v2, s14, v2, v3
	s_waitcnt vmcnt(5)
	ds_write_b128 v2, v[132:135]

; template <int MODE>
; DI void flash_pass(AState& st, const bf16x8* qf, u64 tmask, u64 wmask,
;                    const bf16_t* kbase, size_t kld, const bf16_t* kpe, const bf16_t* vtbase, const float* fbias,
;                    int tq, u64 mysel, bf16_t* smem) {
;     ...
;     if (t1 < 0) return true;
;     t0 = t1; t1 = t2; t2 = t3; t3 = t4; stg = stg == 2 ? 0 : stg + 1;
;     return false;
;   };
;   for (;;) {
;     if (step(S0{})) break;
;     if (step(S1{})) break;
.LBB0_773:
	s_or_b64 exec, exec, s[14:15]
	s_and_b64 s[8:9], s[8:9], exec
	s_cselect_b32 s8, -1, s19
	s_cmp_lt_i32 s16, 0
	s_cselect_b64 s[14:15], -1, 0
	s_mov_b32 s21, -1
	s_and_b64 vcc, exec, s[14:15]
	s_waitcnt lgkmcnt(0)
	s_barrier
	s_cbranch_vccnz .LBB0_775
	s_and_b64 s[12:13], s[12:13], exec
	s_cselect_b32 s9, -1, s20
	s_add_i32 s12, s18, 1
	s_nop 0
	s_and_b32 s18, s12, 3
	s_mov_b32 s21, s17
	s_mov_b32 s17, s8
	s_mov_b32 s8, s9
	s_branch .LBB0_776

; template <int MODE>
; DI void flash_pass(AState& st, const bf16x8* qf, u64 tmask, u64 wmask,
;                    const bf16_t* kbase, size_t kld, const bf16_t* kpe, const bf16_t* vtbase, const float* fbias,
;                    int tq, u64 mysel, bf16_t* smem) {
;     ...
;   auto sstore = [&](int stg, auto setc) {
;     constexpr int S = decltype(setc)::value;
;     bf16_t* Ks = smem + stg * C::STAGE; bf16_t* Vs = Ks + C::K_ELEMS;
; #pragma unroll
;     for (int i = 0; i < C::KCH; ++i) {
;       const int c = tid + NTHR * i;
;       if (c < C::NKC) {
;         if constexpr (MODE == M_MLA) { const int key = c / 12, dc = c % 12; *(u32x4*)(Ks + key * C::KLD + dc * 8) = rk[S][i]; }
;         else { const int key = c >> 3, dc = c & 7; *(u32x4*)(Ks + key * C::KLD + dc * 8) = rk[S][i]; }
;       }
;     ...
;   auto step = [&](auto setc) -> bool {
;     const int t4 = pop();
;     sstore(stg == 0 ? 2 : stg - 1, setc);
.LBB0_1714:
	s_mul_i32 s6, s82, 0x2480
	s_xor_b32 s4, s82, 2
	s_mul_i32 s4, s4, 0x2480
	s_nop 0
	s_lshl_b32 s7, s4, 1
	s_and_saveexec_b64 s[4:5], s[0:1]
	s_cbranch_execz .LBB0_1716
	v_add3_u32 v0, s7, v167, v148
	s_waitcnt vmcnt(2)
	ds_write_b128 v0, v[132:135]

; template <int MODE>
; DI void flash_pass(AState& st, const bf16x8* qf, u64 tmask, u64 wmask,
;                    const bf16_t* kbase, size_t kld, const bf16_t* kpe, const bf16_t* vtbase, const float* fbias,
;                    int tq, u64 mysel, bf16_t* smem) {
;     ...
;   auto step = [&](auto setc) -> bool {
;     const int t4 = pop();
;     sstore(stg == 0 ? 2 : stg - 1, setc);
;     ...
;     compute(t0, stg);
;     __syncthreads();
;     if (t1 < 0) return true;
;     t0 = t1; t1 = t2; t2 = t3; t3 = t4; stg = stg == 2 ? 0 : stg + 1;
.LBB0_1727:
	s_or_b64 exec, exec, s[80:81]
	s_cmp_lt_i32 s97, 0
	s_mov_b64 s[4:5], -1
	s_nop 0
	s_nop 0
	s_cbranch_scc1 .Lxb6
	s_add_i32 s4, s82, 1
	s_nop 0
	s_and_b32 s89, s4, 3
	s_mul_i32 s6, s89, 0x2480
	s_xor_b32 s4, s89, 2
	s_mul_i32 s4, s4, 0x2480
	s_nop 0
	s_lshl_b32 s7, s4, 1
	s_and_saveexec_b64 s[4:5], s[0:1]
	s_cbranch_execz .LBB0_1730
	v_add3_u32 v0, s7, v167, v148
	s_waitcnt vmcnt(5)
	ds_write_b128 v0, v[136:139]
